# seam 0: one L2 write-back per XCD (two-phase counter barrier with an elected flusher per XCC_ID) instead of one per workgroup
# speedup vs baseline: 1.0116x; 1.0116x over previous
; #define LAS __attribute__((address_space(3)))
; __global__ void __launch_bounds__(NWAVES * 64, 2) mega_fwd(Args a) {
;     extern __shared__ __attribute__((aligned(16))) unsigned char lds[];
;     cg::grid_group grid = cg::this_grid();
;     const int tid = threadIdx.x, lane = tid & 63, wave = __builtin_amdgcn_readfirstlane(tid >> 6);
;     const int G = gridDim.x, bx = blockIdx.x;
;     const int vcu = (G % 8 == 0) ? (bx % 8) * (G / 8) + bx / 8 : bx;
;     unsigned char* ws = a.ws;
;     bf16 *Win_t = (bf16*)(ws + WS_WIN), *Wout_t = (bf16*)(ws + WS_WOUT), *XN = (bf16*)(ws + WS_XN), *Y = (bf16*)(ws + WS_Y);
;     bf16 *QA = (bf16*)(ws + WS_QA), *KA = (bf16*)(ws + WS_KA), *VA = (bf16*)(ws + WS_VA), *GA = (bf16*)(ws + WS_GA), *QB = (bf16*)(ws + WS_QB), *KB = (bf16*)(ws + WS_KB), *VB = (bf16*)(ws + WS_VB), *GB = (bf16*)(ws + WS_GB);
;     bf16 *OA1 = (bf16*)(ws + WS_OA1), *OA2 = (bf16*)(ws + WS_OA2), *OB = (bf16*)(ws + WS_OB);
;     const int lo = a.ph_lo, hi = a.ph_hi;
;     ...
;     unsigned* const ctr1 = (unsigned*)ws, * const ctr2 = (unsigned*)ws + 64, * const gflag = (unsigned*)ws + 128, * const qctr = (unsigned*)ws + 192;
;     ...
;     if (IN(0)) for (int rep_ = 0; rep_ < REP_P0; ++rep_) {
;         LAS float* scr = (LAS float*)((LAS unsigned char*)lds + wave * 16384);
;         const int gw = vcu * NWAVES + wave, NGW = G * NWAVES;
.LBB0_2:
	v_cmp_eq_u32_e32 vcc, 0, v229
	s_mov_b64 s[100:101], exec
	s_and_b64 exec, exec, vcc
	s_cbranch_execz .Lh_t0
	s_getreg_b32 s32, hwreg(HW_REG_XCC_ID, 0, 4)
	s_lshl_b32 s32, 1, s32
	v_mov_b32_e32 v252, 0
	v_mov_b32_e32 v253, s32
	global_atomic_or v252, v253, s[76:77] offset:904
.Lh_t0:
	s_mov_b64 exec, s[100:101]
	s_add_u32 s6, s76, 0x200000
	s_addc_u32 s7, s77, 0
	s_add_u32 s72, s76, 0x1c00000
	s_addc_u32 s73, s77, 0
	s_load_dwordx16 s[56:71], s[0:1], 0x40
	s_cmp_lt_i32 s78, 1
	s_cselect_b64 s[0:1], -1, 0
	s_cmp_gt_i32 s79, 0
	s_cselect_b64 s[4:5], -1, 0
	s_and_b64 s[4:5], s[0:1], s[4:5]
	s_andn2_b64 vcc, exec, s[4:5]
	v_and_b32_e32 v231, 63, v229
	s_cbranch_vccnz .LBB0_39
	s_lshr_b32 s17, s8, 6
	s_lshl_b32 s0, s30, 3
	s_add_i32 s8, s0, s17
	s_lshl_b32 s10, s83, 3
	s_cmpk_gt_i32 s8, 0x20ff
	s_cbranch_scc1 .LBB0_16
	s_cmpk_lt_i32 s8, 0x1900
	v_readlane_b32 s36, v254, 0
	s_cselect_b64 s[12:13], -1, 0
	v_readlane_b32 s42, v254, 6
	v_readlane_b32 s43, v254, 7
	s_movk_i32 s11, 0x1900
	s_and_b64 vcc, exec, s[12:13]
	s_mov_b32 s9, s8
	s_mov_b64 s[0:1], s[6:7]
	s_mov_b64 s[14:15], s[42:43]
	v_readlane_b32 s37, v254, 1
	v_readlane_b32 s38, v254, 2
	v_readlane_b32 s39, v254, 3
	v_readlane_b32 s40, v254, 4
	v_readlane_b32 s41, v254, 5
	v_readlane_b32 s44, v254, 8
	v_readlane_b32 s45, v254, 9
	v_readlane_b32 s46, v254, 10
	v_readlane_b32 s47, v254, 11
	v_readlane_b32 s48, v254, 12
	v_readlane_b32 s49, v254, 13
	v_readlane_b32 s50, v254, 14
	v_readlane_b32 s51, v254, 15
	s_cbranch_vccnz .LBB0_6
	s_add_i32 s9, s8, 0xffffe700
	s_movk_i32 s11, 0x800
	s_mov_b64 s[0:1], s[72:73]
	s_waitcnt lgkmcnt(0)
	s_mov_b64 s[14:15], s[68:69]

; __device__ __forceinline__ void grid_bar(unsigned* ctr, unsigned target) {
;     asm volatile("s_waitcnt vmcnt(0)" ::: "memory");
;     __syncthreads();
;     if (threadIdx.x == 0) {
;         __builtin_amdgcn_fence(__ATOMIC_RELEASE, "agent");
;         asm volatile("s_waitcnt vmcnt(0)" ::: "memory");
;         __hip_atomic_fetch_add(ctr, 1u, __ATOMIC_RELAXED, __HIP_MEMORY_SCOPE_AGENT);
;         while (__hip_atomic_load(ctr, __ATOMIC_RELAXED, __HIP_MEMORY_SCOPE_AGENT) < target) __builtin_amdgcn_s_sleep(2);
;         __builtin_amdgcn_fence(__ATOMIC_ACQUIRE, "agent");
;         asm volatile("s_waitcnt vmcnt(0)" ::: "memory");
;     }
;     __syncthreads();
; }
.LBB0_39:
	s_cmp_gt_i32 s79, 1
	s_cselect_b64 s[0:1], -1, 0
	s_and_b64 s[4:5], s[4:5], s[0:1]
	s_andn2_b64 vcc, exec, s[4:5]
	s_cbranch_vccnz .LBB0_61
	s_cmp_gt_i32 s78, -1
	s_mov_b64 s[4:5], -1
	s_waitcnt vmcnt(0)
	v_cmp_eq_u32_e32 vcc, 0, v229
	s_waitcnt lgkmcnt(0)
	s_barrier
	s_and_saveexec_b64 s[4:5], vcc
	s_cbranch_execz .LBB0_47
	s_getreg_b32 s8, hwreg(HW_REG_XCC_ID, 0, 4)
	s_lshl_b32 s9, s8, 2
	v_mov_b32_e32 v240, 0
	v_mov_b32_e32 v241, 1
	global_atomic_add v240, v241, s[76:77] offset:896
.Lh0_a1:
	global_load_dword v242, v240, s[76:77] offset:896 sc1
	s_waitcnt vmcnt(0)
	v_cmp_gt_u32_e32 vcc, s83, v242
	s_cbranch_vccz .Lh0_a2
	s_sleep 2
	s_branch .Lh0_a1
.Lh0_a2:
	v_mov_b32_e32 v243, s9
	global_atomic_add v244, v243, v241, s[76:77] offset:352 sc0
	global_load_dword v245, v240, s[76:77] offset:904 sc1
	s_waitcnt vmcnt(0)
	v_readfirstlane_b32 s10, v245
	s_nop 3
	s_bcnt1_i32_b32 s10, s10
	v_cmp_ne_u32_e32 vcc, 0, v244
	s_cbranch_vccnz .Lh0_a3
	buffer_wbl2 sc1
	s_waitcnt vmcnt(0)
	global_atomic_add v240, v241, s[76:77] offset:900
.Lh0_a3:
	global_load_dword v242, v240, s[76:77] offset:900 sc1
	s_waitcnt vmcnt(0)
	v_readfirstlane_b32 s11, v242
	s_nop 3
	s_cmp_lt_u32 s11, s10
	s_cbranch_scc0 .Lh0_done
	s_sleep 2
	s_branch .Lh0_a3
